# speedup vs baseline: 1.0035x; 1.0020x over previous
; __device__ __forceinline__ float bflo(unsigned u) { return __uint_as_float(u << 16); }
; __device__ __forceinline__ float bfhi(unsigned u) { return __uint_as_float(u & 0xffff0000u); }
; __device__ __forceinline__ void phase_fox_attn(const Params& p, char* smem) {
;     ...
; #pragma unroll
;     for (int qb = 0; qb < 2; ++qb) {
;       float lt = l[qb];
;       lt += __shfl_xor(lt, 16);
;       lt += __shfl_xor(lt, 32);
;       const float inv = 1.f / lt;
;       const long tok = tokbase + q0 + wave * 32 + qb * 16 + lr;
; #pragma unroll
;       for (int db = 0; db < 8; ++db) {
;         const int col = h * 128 + db * 16 + g * 4;
;         u32x2 gv = *(const u32x2*)(G + tok * 1024 + col);
;         u32x2 ov;
;         ov.x = pack2(o[db][qb][0] * inv * bflo(gv.x), o[db][qb][1] * inv * bfhi(gv.x));
;         ov.y = pack2(o[db][qb][2] * inv * bflo(gv.y), o[db][qb][3] * inv * bfhi(gv.y));
;         *(u32x2*)(M + tok * 1024 + col) = ov;
;       }
;     }
.LBB0_195:
	v_mbcnt_hi_u32_b32 v126, -1, v156
	v_and_b32_e32 v128, 64, v126
	v_xor_b32_e32 v127, 16, v126
	v_add_u32_e32 v128, 64, v128
	v_xor_b32_e32 v129, 32, v126
	v_or_b32_e32 v104, s2, v64
	v_lshl_add_u64 v[66:67], s[26:27], 0, v[110:111]
	v_lshlrev_b64 v[64:65], 1, v[104:105]
	v_lshl_add_u64 v[66:67], v[66:67], 0, v[64:65]
	global_load_dwordx2 v[70:71], v[66:67], off
	global_load_dwordx2 v[72:73], v[66:67], off offset:32
	global_load_dwordx2 v[74:75], v[66:67], off offset:64
	global_load_dwordx2 v[76:77], v[66:67], off offset:96
	global_load_dwordx2 v[78:79], v[66:67], off offset:128
	v_cmp_lt_i32_e32 vcc, v127, v128
	v_lshl_add_u64 v[80:81], s[26:27], 0, v[106:107]
	s_waitcnt vmcnt(0)
	v_and_b32_e32 v95, 0xffff0000, v74
	v_cndmask_b32_e32 v68, v126, v127, vcc
	v_cmp_lt_i32_e32 vcc, v129, v128
	v_lshlrev_b32_e32 v89, 2, v68
	ds_bpermute_b32 v84, v89, v109
	v_cndmask_b32_e32 v82, v126, v129, vcc
	v_lshlrev_b32_e32 v100, 2, v82
	global_load_dwordx2 v[82:83], v[66:67], off offset:160
	v_lshl_add_u64 v[68:69], s[42:43], 0, v[110:111]
	s_waitcnt lgkmcnt(0)
	v_add_f32_e32 v88, v109, v84
	v_lshl_add_u64 v[84:85], v[68:69], 0, v[64:65]
	v_lshl_add_u64 v[68:69], v[80:81], 0, v[64:65]
	global_load_dwordx2 v[80:81], v[66:67], off offset:192
	global_load_dwordx2 v[86:87], v[66:67], off offset:224
	ds_bpermute_b32 v90, v100, v88
	v_lshlrev_b32_e32 v96, 16, v76
	v_and_b32_e32 v97, 0xffff0000, v76
	v_lshlrev_b32_e32 v76, 16, v77
	v_and_b32_e32 v77, 0xffff0000, v77
	s_waitcnt lgkmcnt(0)
	v_add_f32_e32 v88, v88, v90
	v_div_scale_f32 v90, s[2:3], v88, v88, 1.0
	v_rcp_f32_e32 v91, v90
	v_div_scale_f32 v92, vcc, 1.0, v88, 1.0
	global_load_dwordx2 v[66:67], v[68:69], off
	v_fma_f32 v93, -v90, v91, 1.0
	v_fmac_f32_e32 v91, v93, v91
	v_mul_f32_e32 v93, v92, v91
	v_fma_f32 v94, -v90, v93, v92
	v_fmac_f32_e32 v93, v94, v91
	v_fma_f32 v90, -v90, v93, v92
	v_div_fmas_f32 v90, v90, v91, v93
	v_div_fixup_f32 v88, v90, v88, 1.0
	v_pk_mul_f32 v[48:49], v[48:49], v[88:89] op_sel_hi:[1,0]
	v_pk_mul_f32 v[50:51], v[50:51], v[88:89] op_sel_hi:[1,0]
	v_pk_mul_f32 v[52:53], v[52:53], v[88:89] op_sel_hi:[1,0]
	v_pk_mul_f32 v[54:55], v[54:55], v[88:89] op_sel_hi:[1,0]
	v_lshlrev_b32_e32 v90, 16, v70
	v_and_b32_e32 v91, 0xffff0000, v70
	v_lshlrev_b32_e32 v70, 16, v71
	v_and_b32_e32 v71, 0xffff0000, v71
	v_lshlrev_b32_e32 v92, 16, v72
	v_and_b32_e32 v93, 0xffff0000, v72
	v_lshlrev_b32_e32 v72, 16, v73
	v_and_b32_e32 v73, 0xffff0000, v73
	v_pk_mul_f32 v[56:57], v[56:57], v[88:89] op_sel_hi:[1,0]
	v_pk_mul_f32 v[58:59], v[58:59], v[88:89] op_sel_hi:[1,0]
	v_pk_mul_f32 v[60:61], v[60:61], v[88:89] op_sel_hi:[1,0]
	v_pk_mul_f32 v[62:63], v[62:63], v[88:89] op_sel_hi:[1,0]
	v_lshlrev_b32_e32 v94, 16, v74
	v_lshlrev_b32_e32 v74, 16, v75
	v_and_b32_e32 v75, 0xffff0000, v75
	v_pk_mul_f32 v[48:49], v[48:49], v[90:91]
	v_pk_mul_f32 v[50:51], v[50:51], v[70:71]
	v_pk_mul_f32 v[52:53], v[52:53], v[92:93]
	v_pk_mul_f32 v[54:55], v[54:55], v[72:73]
	v_pk_mul_f32 v[56:57], v[56:57], v[94:95]
	v_pk_mul_f32 v[58:59], v[58:59], v[74:75]
	v_pk_mul_f32 v[60:61], v[60:61], v[96:97]
	v_pk_mul_f32 v[62:63], v[62:63], v[76:77]
	v_cvt_pk_bf16_f32 v48, v48, v49
	v_cvt_pk_bf16_f32 v49, v50, v51
	v_cvt_pk_bf16_f32 v50, v52, v53
	v_cvt_pk_bf16_f32 v51, v54, v55
	v_pk_mul_f32 v[44:45], v[44:45], v[88:89] op_sel_hi:[1,0]
	v_lshlrev_b32_e32 v98, 16, v78
	v_cvt_pk_bf16_f32 v52, v56, v57
	v_cvt_pk_bf16_f32 v53, v58, v59
	v_cvt_pk_bf16_f32 v54, v60, v61
	v_cvt_pk_bf16_f32 v55, v62, v63
	global_store_dwordx2 v[84:85], v[48:49], off
	global_store_dwordx2 v[84:85], v[50:51], off offset:32
	global_store_dwordx2 v[84:85], v[52:53], off offset:64
	global_store_dwordx2 v[84:85], v[54:55], off offset:96
	v_and_b32_e32 v99, 0xffff0000, v78
	v_pk_mul_f32 v[46:47], v[46:47], v[88:89] op_sel_hi:[1,0]
	v_lshlrev_b32_e32 v50, 16, v79
	v_and_b32_e32 v51, 0xffff0000, v79
	v_pk_mul_f32 v[44:45], v[44:45], v[98:99]
	v_pk_mul_f32 v[46:47], v[46:47], v[50:51]
	v_cvt_pk_bf16_f32 v44, v44, v45
	v_cvt_pk_bf16_f32 v45, v46, v47
	global_store_dwordx2 v[84:85], v[44:45], off offset:128
	v_pk_mul_f32 v[40:41], v[40:41], v[88:89] op_sel_hi:[1,0]
	v_pk_mul_f32 v[42:43], v[42:43], v[88:89] op_sel_hi:[1,0]
	v_pk_mul_f32 v[36:37], v[36:37], v[88:89] op_sel_hi:[1,0]
	v_pk_mul_f32 v[38:39], v[38:39], v[88:89] op_sel_hi:[1,0]
	global_load_dwordx2 v[48:49], v[68:69], off offset:32
	global_load_dwordx2 v[46:47], v[68:69], off offset:64
	v_pk_mul_f32 v[32:33], v[32:33], v[88:89] op_sel_hi:[1,0]
	s_waitcnt vmcnt(10)
	v_lshlrev_b32_e32 v44, 16, v82
	v_and_b32_e32 v45, 0xffff0000, v82
	v_pk_mul_f32 v[40:41], v[40:41], v[44:45]
	v_lshlrev_b32_e32 v44, 16, v83
	v_and_b32_e32 v45, 0xffff0000, v83
	v_pk_mul_f32 v[42:43], v[42:43], v[44:45]
	v_cvt_pk_bf16_f32 v40, v40, v41
	v_cvt_pk_bf16_f32 v41, v42, v43
	s_waitcnt vmcnt(9)
	v_lshlrev_b32_e32 v42, 16, v80
	v_and_b32_e32 v43, 0xffff0000, v80
	v_pk_mul_f32 v[36:37], v[36:37], v[42:43]
	v_lshlrev_b32_e32 v42, 16, v81
	v_and_b32_e32 v43, 0xffff0000, v81
	v_pk_mul_f32 v[38:39], v[38:39], v[42:43]
	ds_bpermute_b32 v42, v89, v108
	v_cvt_pk_bf16_f32 v36, v36, v37
	v_cvt_pk_bf16_f32 v37, v38, v39
	s_waitcnt vmcnt(8)
; __device__ __forceinline__ float bflo(unsigned u) { return __uint_as_float(u << 16); }
; __device__ __forceinline__ float bfhi(unsigned u) { return __uint_as_float(u & 0xffff0000u); }
; __device__ __forceinline__ void phase_fox_attn(const Params& p, char* smem) {
;     ...
; #pragma unroll
;     for (int qb = 0; qb < 2; ++qb) {
;       float lt = l[qb];
;       lt += __shfl_xor(lt, 16);
;       lt += __shfl_xor(lt, 32);
;       const float inv = 1.f / lt;
;       const long tok = tokbase + q0 + wave * 32 + qb * 16 + lr;
; #pragma unroll
;       for (int db = 0; db < 8; ++db) {
;         const int col = h * 128 + db * 16 + g * 4;
;         u32x2 gv = *(const u32x2*)(G + tok * 1024 + col);
;         u32x2 ov;
;         ov.x = pack2(o[db][qb][0] * inv * bflo(gv.x), o[db][qb][1] * inv * bfhi(gv.x));
;         ov.y = pack2(o[db][qb][2] * inv * bflo(gv.y), o[db][qb][3] * inv * bfhi(gv.y));
;         *(u32x2*)(M + tok * 1024 + col) = ov;
;       }
;     }
	v_lshlrev_b32_e32 v38, 16, v86
	v_and_b32_e32 v39, 0xffff0000, v86
	v_pk_mul_f32 v[32:33], v[32:33], v[38:39]
	global_store_dwordx2 v[84:85], v[40:41], off offset:160
	v_cvt_pk_bf16_f32 v32, v32, v33
	s_waitcnt lgkmcnt(0)
	v_add_f32_e32 v33, v108, v42
	ds_bpermute_b32 v44, v100, v33
	global_load_dwordx2 v[40:41], v[68:69], off offset:96
	v_pk_mul_f32 v[34:35], v[34:35], v[88:89] op_sel_hi:[1,0]
	global_store_dwordx2 v[84:85], v[36:37], off offset:192
	global_load_dwordx2 v[36:37], v[68:69], off offset:128
	s_waitcnt lgkmcnt(0)
	v_add_f32_e32 v44, v33, v44
	v_div_scale_f32 v45, s[2:3], v44, v44, 1.0
	v_rcp_f32_e32 v50, v45
	v_lshlrev_b32_e32 v38, 16, v87
	v_and_b32_e32 v39, 0xffff0000, v87
	v_pk_mul_f32 v[34:35], v[34:35], v[38:39]
	global_load_dwordx2 v[42:43], v[68:69], off offset:160
	v_cvt_pk_bf16_f32 v33, v34, v35
	global_store_dwordx2 v[84:85], v[32:33], off offset:224
	v_fma_f32 v32, -v45, v50, 1.0
	v_fmac_f32_e32 v50, v32, v50
	v_div_scale_f32 v34, vcc, 1.0, v44, 1.0
	v_mul_f32_e32 v35, v34, v50
	global_load_dwordx2 v[32:33], v[68:69], off offset:192
	v_fma_f32 v38, -v45, v35, v34
	v_fmac_f32_e32 v35, v38, v50
	v_fma_f32 v34, -v45, v35, v34
	v_div_fmas_f32 v34, v34, v50, v35
	v_div_fixup_f32 v34, v34, v44, 1.0
	global_load_dwordx2 v[44:45], v[68:69], off offset:224
	v_pk_mul_f32 v[28:29], v[28:29], v[34:35] op_sel_hi:[1,0]
	s_waitcnt vmcnt(15)
	v_lshlrev_b32_e32 v50, 16, v66
	v_and_b32_e32 v51, 0xffff0000, v66
	v_pk_mul_f32 v[28:29], v[28:29], v[50:51]
	v_pk_mul_f32 v[30:31], v[30:31], v[34:35] op_sel_hi:[1,0]
	v_lshlrev_b32_e32 v50, 16, v67
	v_and_b32_e32 v51, 0xffff0000, v67
	v_lshl_add_u64 v[38:39], s[42:43], 0, v[106:107]
	v_pk_mul_f32 v[30:31], v[30:31], v[50:51]
	v_cvt_pk_bf16_f32 v28, v28, v29
	v_cvt_pk_bf16_f32 v29, v30, v31
	v_lshl_add_u64 v[30:31], v[38:39], 0, v[64:65]
	global_store_dwordx2 v[30:31], v[28:29], off
	v_pk_mul_f32 v[24:25], v[24:25], v[34:35] op_sel_hi:[1,0]
	v_pk_mul_f32 v[26:27], v[26:27], v[34:35] op_sel_hi:[1,0]
	v_pk_mul_f32 v[20:21], v[20:21], v[34:35] op_sel_hi:[1,0]
	v_pk_mul_f32 v[22:23], v[22:23], v[34:35] op_sel_hi:[1,0]
	v_pk_mul_f32 v[16:17], v[16:17], v[34:35] op_sel_hi:[1,0]
	v_pk_mul_f32 v[18:19], v[18:19], v[34:35] op_sel_hi:[1,0]
	v_pk_mul_f32 v[12:13], v[12:13], v[34:35] op_sel_hi:[1,0]
	v_pk_mul_f32 v[14:15], v[14:15], v[34:35] op_sel_hi:[1,0]
	v_pk_mul_f32 v[8:9], v[8:9], v[34:35] op_sel_hi:[1,0]
	v_pk_mul_f32 v[10:11], v[10:11], v[34:35] op_sel_hi:[1,0]
	v_pk_mul_f32 v[4:5], v[4:5], v[34:35] op_sel_hi:[1,0]
	v_pk_mul_f32 v[6:7], v[6:7], v[34:35] op_sel_hi:[1,0]
	v_pk_mul_f32 v[0:1], v[0:1], v[34:35] op_sel_hi:[1,0]
	v_pk_mul_f32 v[2:3], v[2:3], v[34:35] op_sel_hi:[1,0]
	s_waitcnt vmcnt(10)
	v_lshlrev_b32_e32 v28, 16, v48
	v_and_b32_e32 v29, 0xffff0000, v48
	v_pk_mul_f32 v[24:25], v[24:25], v[28:29]
	v_lshlrev_b32_e32 v28, 16, v49
	v_and_b32_e32 v29, 0xffff0000, v49
	v_pk_mul_f32 v[26:27], v[26:27], v[28:29]
	v_cvt_pk_bf16_f32 v24, v24, v25
	v_cvt_pk_bf16_f32 v25, v26, v27
	global_store_dwordx2 v[30:31], v[24:25], off offset:32
	s_waitcnt vmcnt(10)
	v_lshlrev_b32_e32 v24, 16, v46
	v_and_b32_e32 v25, 0xffff0000, v46
	v_pk_mul_f32 v[20:21], v[20:21], v[24:25]
	v_lshlrev_b32_e32 v24, 16, v47
	v_and_b32_e32 v25, 0xffff0000, v47
	v_pk_mul_f32 v[22:23], v[22:23], v[24:25]
	v_cvt_pk_bf16_f32 v20, v20, v21
	v_cvt_pk_bf16_f32 v21, v22, v23
	global_store_dwordx2 v[30:31], v[20:21], off offset:64
	v_readlane_b32 s2, v225, 2
	s_add_i32 s1, s1, s2
	s_cmpk_gt_i32 s1, 0xfff
	v_readlane_b32 s3, v225, 3
	s_waitcnt vmcnt(9)
	v_lshlrev_b32_e32 v20, 16, v40
	v_and_b32_e32 v21, 0xffff0000, v40
	v_pk_mul_f32 v[16:17], v[16:17], v[20:21]
	v_lshlrev_b32_e32 v20, 16, v41
	v_and_b32_e32 v21, 0xffff0000, v41
	v_pk_mul_f32 v[18:19], v[18:19], v[20:21]
	v_cvt_pk_bf16_f32 v16, v16, v17
	v_cvt_pk_bf16_f32 v17, v18, v19
	global_store_dwordx2 v[30:31], v[16:17], off offset:96
	s_waitcnt vmcnt(8)
	v_lshlrev_b32_e32 v16, 16, v36
	v_and_b32_e32 v17, 0xffff0000, v36
	v_pk_mul_f32 v[12:13], v[12:13], v[16:17]
	v_lshlrev_b32_e32 v16, 16, v37
	v_and_b32_e32 v17, 0xffff0000, v37
	v_pk_mul_f32 v[14:15], v[14:15], v[16:17]
	v_cvt_pk_bf16_f32 v12, v12, v13
	v_cvt_pk_bf16_f32 v13, v14, v15
	global_store_dwordx2 v[30:31], v[12:13], off offset:128
	s_waitcnt vmcnt(8)
	v_lshlrev_b32_e32 v12, 16, v42
	v_and_b32_e32 v13, 0xffff0000, v42
	v_pk_mul_f32 v[8:9], v[8:9], v[12:13]
	v_lshlrev_b32_e32 v12, 16, v43
	v_and_b32_e32 v13, 0xffff0000, v43
	v_pk_mul_f32 v[10:11], v[10:11], v[12:13]
	v_cvt_pk_bf16_f32 v8, v8, v9
	v_cvt_pk_bf16_f32 v9, v10, v11
	global_store_dwordx2 v[30:31], v[8:9], off offset:160
	s_waitcnt vmcnt(7)
	v_lshlrev_b32_e32 v8, 16, v32
	v_and_b32_e32 v9, 0xffff0000, v32
	v_pk_mul_f32 v[4:5], v[4:5], v[8:9]
	v_lshlrev_b32_e32 v8, 16, v33
	v_and_b32_e32 v9, 0xffff0000, v33
	v_pk_mul_f32 v[6:7], v[6:7], v[8:9]
	v_cvt_pk_bf16_f32 v4, v4, v5
	v_cvt_pk_bf16_f32 v5, v6, v7
	global_store_dwordx2 v[30:31], v[4:5], off offset:192
	s_waitcnt vmcnt(7)
	v_lshlrev_b32_e32 v4, 16, v44
	v_and_b32_e32 v5, 0xffff0000, v44
	v_pk_mul_f32 v[0:1], v[0:1], v[4:5]
	v_lshlrev_b32_e32 v4, 16, v45
	v_and_b32_e32 v5, 0xffff0000, v45
	v_pk_mul_f32 v[2:3], v[2:3], v[4:5]
	v_cvt_pk_bf16_f32 v0, v0, v1
	v_cvt_pk_bf16_f32 v1, v2, v3
	global_store_dwordx2 v[30:31], v[0:1], off offset:224
	s_cbranch_scc1 .LBB0_205

; __device__ __forceinline__ void phase_fox_attn(const Params& p, char* smem) {
;     ...
;       f32x4 s[4][2];
; #pragma unroll
;       for (int kb = 0; kb < 4; ++kb) { s[kb][0] = (f32x4){0.f, 0.f, 0.f, 0.f}; s[kb][1] = (f32x4){0.f, 0.f, 0.f, 0.f}; }
;       int kb_ = kbase, vb_ = vbase;
;       asm volatile("" : "+v"(kb_), "+v"(vb_));
;       __builtin_amdgcn_s_setprio(1);
; #pragma unroll
;       for (int ks = 0; ks < 4; ++ks) {
;         const int ko = kb_ ^ (ks << 6);
; #pragma unroll
;         for (int kb = 0; kb < 4; ++kb) {
;           bf16x8 a = *(const bf16x8*)(sK + kb * 4096 + ko);
;           s[kb][0] = __builtin_amdgcn_mfma_f32_16x16x32_bf16(a, qf[0][ks], s[kb][0], 0, 0, 0);
;           s[kb][1] = __builtin_amdgcn_mfma_f32_16x16x32_bf16(a, qf[1][ks], s[kb][1], 0, 0, 0);
;         }
;       }
;       __builtin_amdgcn_s_setprio(0);
;       const bool diag = (t >= nkv - 2);
;       float mx2[2];
; #pragma unroll
;       for (int qb = 0; qb < 2; ++qb) {
;         const int qpos = q0 + wave * 32 + qb * 16 + lr;
;         float mx = -INFINITY;
; #pragma unroll
;         for (int kb = 0; kb < 4; ++kb)
; #pragma unroll
;           for (int r = 0; r < 4; ++r) {
;             int kl = kb * 16 + g * 4 + r;
;             float v = s[kb][qb][r] + (ct[qb] - sCt[kl]);
;             if (diag && (kv0 + kl > qpos)) v = -INFINITY;
;             s[kb][qb][r] = v;
;             mx = fmaxf(mx, v);
;           }
.LBB0_203:
	s_lshl_b32 s4, s87, 14
	s_add_i32 s6, s4, 0
	v_mov_b32_e32 v139, v132
	v_mov_b32_e32 v104, v133
	s_setprio 1
	v_add_u32_e32 v143, s6, v139
	ds_read_b128 v[96:99], v143
	ds_read_b128 v[100:103], v143 offset:4096
	ds_read_b128 v[150:153], v143 offset:8192
	ds_read_b128 v[158:161], v143 offset:12288
	v_xad_u32 v143, v139, 64, s6
	ds_read_b128 v[170:173], v143
	ds_read_b128 v[174:177], v143 offset:4096
	s_waitcnt lgkmcnt(0)
	v_mfma_f32_16x16x32_bf16 v[126:129], v[96:99], v[92:95], 0
	v_mfma_f32_16x16x32_bf16 v[96:99], v[96:99], v[76:79], 0
	v_mfma_f32_16x16x32_bf16 v[146:149], v[100:103], v[92:95], 0
	v_mfma_f32_16x16x32_bf16 v[100:103], v[100:103], v[76:79], 0
	v_mfma_f32_16x16x32_bf16 v[126:129], v[170:173], v[64:67], v[126:129]
	v_mfma_f32_16x16x32_bf16 v[96:99], v[170:173], v[80:83], v[96:99]
	v_mfma_f32_16x16x32_bf16 v[146:149], v[174:177], v[64:67], v[146:149]
	v_mfma_f32_16x16x32_bf16 v[100:103], v[174:177], v[80:83], v[100:103]
	ds_read_b128 v[170:173], v143 offset:8192
	ds_read_b128 v[174:177], v143 offset:12288
	v_xor_b32_e32 v143, 0x80, v139
	v_add_u32_e32 v143, s6, v143
	v_mfma_f32_16x16x32_bf16 v[162:165], v[150:153], v[92:95], 0
	v_xor_b32_e32 v139, 0xc0, v139
	v_add_u32_e32 v139, s6, v139
	v_mfma_f32_16x16x32_bf16 v[150:153], v[150:153], v[76:79], 0
	v_mfma_f32_16x16x32_bf16 v[166:169], v[158:161], v[92:95], 0
	v_mfma_f32_16x16x32_bf16 v[158:161], v[158:161], v[76:79], 0
	s_waitcnt lgkmcnt(0)
	v_mfma_f32_16x16x32_bf16 v[162:165], v[170:173], v[64:67], v[162:165]
	v_mfma_f32_16x16x32_bf16 v[150:153], v[170:173], v[80:83], v[150:153]
	v_mfma_f32_16x16x32_bf16 v[166:169], v[174:177], v[64:67], v[166:169]
	v_mfma_f32_16x16x32_bf16 v[158:161], v[174:177], v[80:83], v[158:161]
	ds_read_b128 v[170:173], v143
	ds_read_b128 v[174:177], v143 offset:4096
	s_waitcnt lgkmcnt(0)
	v_mfma_f32_16x16x32_bf16 v[126:129], v[170:173], v[68:71], v[126:129]
	v_mfma_f32_16x16x32_bf16 v[96:99], v[170:173], v[84:87], v[96:99]
	v_mfma_f32_16x16x32_bf16 v[146:149], v[174:177], v[68:71], v[146:149]
	v_mfma_f32_16x16x32_bf16 v[100:103], v[174:177], v[84:87], v[100:103]
	ds_read_b128 v[170:173], v143 offset:8192
	ds_read_b128 v[174:177], v143 offset:12288
	s_waitcnt lgkmcnt(0)
	v_mfma_f32_16x16x32_bf16 v[162:165], v[170:173], v[68:71], v[162:165]
	v_mfma_f32_16x16x32_bf16 v[150:153], v[170:173], v[84:87], v[150:153]
	v_mfma_f32_16x16x32_bf16 v[166:169], v[174:177], v[68:71], v[166:169]
	v_mfma_f32_16x16x32_bf16 v[158:161], v[174:177], v[84:87], v[158:161]
	ds_read_b128 v[170:173], v139
	ds_read_b128 v[174:177], v139 offset:4096
	s_waitcnt lgkmcnt(0)
	v_mfma_f32_16x16x32_bf16 v[178:181], v[170:173], v[72:75], v[126:129]
	v_mfma_f32_16x16x32_bf16 v[170:173], v[170:173], v[88:91], v[96:99]
	s_nop 2
	ds_read_b128 v[96:99], v139 offset:8192
	ds_read_b128 v[126:129], v139 offset:12288
	v_mfma_f32_16x16x32_bf16 v[182:185], v[174:177], v[72:75], v[146:149]
	v_mfma_f32_16x16x32_bf16 v[174:177], v[174:177], v[88:91], v[100:103]
	s_waitcnt lgkmcnt(0)
	v_mfma_f32_16x16x32_bf16 v[162:165], v[96:99], v[72:75], v[162:165]
	v_mfma_f32_16x16x32_bf16 v[100:103], v[96:99], v[88:91], v[150:153]
	v_mfma_f32_16x16x32_bf16 v[166:169], v[126:129], v[72:75], v[166:169]
	v_mfma_f32_16x16x32_bf16 v[96:99], v[126:129], v[88:91], v[158:161]
	s_setprio 0
	s_nop 1
	v_lshl_add_u32 v151, s87, 8, v136
	ds_read_b128 v[186:189], v151
	ds_read_b128 v[190:193], v151 offset:64
	v_add_u32_e32 v159, s86, v123
	s_cmp_ge_i32 s84, s3
	v_add_u32_e32 v160, 0xfc0, v159
	s_cselect_b64 s[4:5], -1, 0
	s_cbranch_scc0 .Lfox_fast
	s_waitcnt lgkmcnt(0)
	v_sub_f32_e32 v139, v130, v186
	v_cmp_gt_i32_e32 vcc, v160, v134
	v_add_f32_e32 v139, v178, v139
	s_and_b64 vcc, s[4:5], vcc
	v_add_u32_e32 v161, 0xfc1, v159
	v_cndmask_b32_e32 v139, v139, v122, vcc
	v_sub_f32_e32 v143, v130, v187
	v_cmp_gt_i32_e32 vcc, v161, v134
	v_add_f32_e32 v143, v179, v143
	s_and_b64 vcc, s[4:5], vcc
	v_add_u32_e32 v196, 0xfc2, v159
	v_cndmask_b32_e32 v143, v143, v122, vcc
	v_sub_f32_e32 v145, v130, v188
	v_cmp_gt_i32_e32 vcc, v196, v134
	v_add_f32_e32 v145, v180, v145
	s_and_b64 vcc, s[4:5], vcc
	v_add_u32_e32 v197, 0xfc3, v159
	v_cndmask_b32_e32 v145, v145, v122, vcc
	v_sub_f32_e32 v146, v130, v189
	v_cmp_gt_i32_e32 vcc, v197, v134
	v_add_f32_e32 v146, v181, v146
	s_and_b64 vcc, s[4:5], vcc
	v_max3_f32 v147, v139, s0, v143
	v_cndmask_b32_e32 v146, v146, v122, vcc
	v_add_u32_e32 v198, 0xfd0, v159
	v_max3_f32 v149, v147, v145, v146
	v_sub_f32_e32 v147, v130, v190
	v_cmp_gt_i32_e32 vcc, v198, v134
	v_add_f32_e32 v147, v182, v147
	s_and_b64 vcc, s[4:5], vcc
	v_add_u32_e32 v199, 0xfd1, v159
	v_cndmask_b32_e32 v147, v147, v122, vcc
	v_sub_f32_e32 v148, v130, v191
	v_cmp_gt_i32_e32 vcc, v199, v134
	v_add_f32_e32 v148, v183, v148
	s_and_b64 vcc, s[4:5], vcc
	v_cndmask_b32_e32 v148, v148, v122, vcc
	v_add_u32_e32 v200, 0xfd2, v159
	ds_read_b128 v[178:181], v151 offset:128
	v_max3_f32 v152, v149, v147, v148
	v_sub_f32_e32 v149, v130, v192
	v_cmp_gt_i32_e32 vcc, v200, v134
	v_add_f32_e32 v149, v184, v149
	s_and_b64 vcc, s[4:5], vcc
	v_add_u32_e32 v201, 0xfd3, v159
	v_cndmask_b32_e32 v149, v149, v122, vcc
	v_sub_f32_e32 v150, v130, v193
	v_cmp_gt_i32_e32 vcc, v201, v134
	v_add_f32_e32 v150, v185, v150
	s_and_b64 vcc, s[4:5], vcc
	v_add_u32_e32 v202, 0xfe0, v159
	v_cndmask_b32_e32 v150, v150, v122, vcc
	ds_read_b128 v[182:185], v151 offset:192
	s_waitcnt lgkmcnt(0)
; __device__ __forceinline__ void phase_fox_attn(const Params& p, char* smem) {
;     ...
; #pragma unroll
;       for (int qb = 0; qb < 2; ++qb) {
;         const int qpos = q0 + wave * 32 + qb * 16 + lr;
;         float mx = -INFINITY;
; #pragma unroll
;         for (int kb = 0; kb < 4; ++kb)
; #pragma unroll
;           for (int r = 0; r < 4; ++r) {
;             int kl = kb * 16 + g * 4 + r;
;             float v = s[kb][qb][r] + (ct[qb] - sCt[kl]);
;             if (diag && (kv0 + kl > qpos)) v = -INFINITY;
;             s[kb][qb][r] = v;
;             mx = fmaxf(mx, v);
;           }
	v_sub_f32_e32 v151, v130, v178
	v_cmp_gt_i32_e32 vcc, v202, v134
	v_add_f32_e32 v151, v162, v151
	s_and_b64 vcc, s[4:5], vcc
	v_add_u32_e32 v203, 0xfe1, v159
	v_max3_f32 v153, v152, v149, v150
	v_cndmask_b32_e32 v151, v151, v122, vcc
	v_sub_f32_e32 v152, v130, v179
	v_cmp_gt_i32_e32 vcc, v203, v134
	v_add_f32_e32 v152, v163, v152
	s_and_b64 vcc, s[4:5], vcc
	v_cndmask_b32_e32 v152, v152, v122, vcc
	v_add_u32_e32 v204, 0xfe2, v159
	v_max3_f32 v155, v153, v151, v152
	v_sub_f32_e32 v153, v130, v180
	v_cmp_gt_i32_e32 vcc, v204, v134
	v_add_f32_e32 v153, v164, v153
	s_and_b64 vcc, s[4:5], vcc
	v_add_u32_e32 v205, 0xfe3, v159
	v_cndmask_b32_e32 v153, v153, v122, vcc
	v_sub_f32_e32 v154, v130, v181
	v_cmp_gt_i32_e32 vcc, v205, v134
	v_add_f32_e32 v154, v165, v154
	s_and_b64 vcc, s[4:5], vcc
	v_cndmask_b32_e32 v154, v154, v122, vcc
	v_add_u32_e32 v206, 0xff0, v159
	v_max3_f32 v158, v155, v153, v154
	v_sub_f32_e32 v155, v130, v182
	v_cmp_gt_i32_e32 vcc, v206, v134
	v_add_f32_e32 v155, v166, v155
	s_and_b64 vcc, s[4:5], vcc
	v_add_u32_e32 v207, 0xff1, v159
	v_cndmask_b32_e32 v155, v155, v122, vcc
	v_sub_f32_e32 v157, v130, v183
	v_cmp_gt_i32_e32 vcc, v207, v134
	v_add_f32_e32 v157, v167, v157
	s_and_b64 vcc, s[4:5], vcc
	v_cndmask_b32_e32 v157, v157, v122, vcc
	v_max3_f32 v162, v158, v155, v157
	v_sub_f32_e32 v158, v130, v184
	v_add_f32_e32 v158, v168, v158
	v_add_u32_e32 v168, 0xff2, v159
	v_cmp_gt_i32_e32 vcc, v168, v134
	v_sub_f32_e32 v163, v130, v185
	s_and_b64 vcc, s[4:5], vcc
	v_add_f32_e32 v163, v169, v163
	v_add_u32_e32 v169, 0xff3, v159
	v_cndmask_b32_e32 v158, v158, v122, vcc
	v_cmp_gt_i32_e32 vcc, v169, v134
	s_and_b64 vcc, s[4:5], vcc
	s_nop 0
	v_cndmask_b32_e32 v159, v163, v122, vcc
	v_max3_f32 v208, v162, v158, v159
	v_sub_f32_e32 v162, v131, v186
	v_cmp_gt_i32_e32 vcc, v160, v135
	v_add_f32_e32 v162, v170, v162
	s_and_b64 vcc, s[4:5], vcc
	v_cndmask_b32_e32 v160, v162, v122, vcc
	v_sub_f32_e32 v162, v131, v187
	v_cmp_gt_i32_e32 vcc, v161, v135
	v_add_f32_e32 v162, v171, v162
	s_and_b64 vcc, s[4:5], vcc
	v_cndmask_b32_e32 v161, v162, v122, vcc
	v_sub_f32_e32 v163, v131, v188
	v_cmp_gt_i32_e32 vcc, v196, v135
	v_add_f32_e32 v163, v172, v163
	s_and_b64 vcc, s[4:5], vcc
	v_cndmask_b32_e32 v164, v163, v122, vcc
	v_sub_f32_e32 v163, v131, v189
	v_cmp_gt_i32_e32 vcc, v197, v135
	v_add_f32_e32 v163, v173, v163
	s_and_b64 vcc, s[4:5], vcc
	v_cndmask_b32_e32 v165, v163, v122, vcc
	v_sub_f32_e32 v163, v131, v190
	v_cmp_gt_i32_e32 vcc, v198, v135
	v_add_f32_e32 v163, v174, v163
	s_and_b64 vcc, s[4:5], vcc
	v_cndmask_b32_e32 v166, v163, v122, vcc
	v_sub_f32_e32 v163, v131, v191
	v_cmp_gt_i32_e32 vcc, v199, v135
	v_max3_f32 v162, v160, s0, v161
	v_add_f32_e32 v163, v175, v163
	s_and_b64 vcc, s[4:5], vcc
	v_max3_f32 v162, v162, v164, v165
	v_cndmask_b32_e32 v167, v163, v122, vcc
	v_max3_f32 v170, v162, v166, v167
	v_sub_f32_e32 v162, v131, v192
	v_cmp_gt_i32_e32 vcc, v200, v135
	v_add_f32_e32 v162, v176, v162
	s_and_b64 vcc, s[4:5], vcc
	v_cndmask_b32_e32 v162, v162, v122, vcc
	v_sub_f32_e32 v163, v131, v193
	v_cmp_gt_i32_e32 vcc, v201, v135
	v_add_f32_e32 v163, v177, v163
	s_and_b64 vcc, s[4:5], vcc
	v_cndmask_b32_e32 v163, v163, v122, vcc
	v_sub_f32_e32 v171, v131, v178
	v_cmp_gt_i32_e32 vcc, v202, v135
	v_add_f32_e32 v100, v100, v171
	s_and_b64 vcc, s[4:5], vcc
	v_cndmask_b32_e32 v100, v100, v122, vcc
	v_sub_f32_e32 v171, v131, v179
	v_cmp_gt_i32_e32 vcc, v203, v135
	v_add_f32_e32 v101, v101, v171
	s_and_b64 vcc, s[4:5], vcc
	v_cndmask_b32_e32 v101, v101, v122, vcc
	v_sub_f32_e32 v171, v131, v180
	v_cmp_gt_i32_e32 vcc, v204, v135
	v_add_f32_e32 v102, v102, v171
	s_and_b64 vcc, s[4:5], vcc
	v_cndmask_b32_e32 v102, v102, v122, vcc
	v_sub_f32_e32 v171, v131, v181
	v_cmp_gt_i32_e32 vcc, v205, v135
	v_add_f32_e32 v103, v103, v171
	s_and_b64 vcc, s[4:5], vcc
	v_cndmask_b32_e32 v103, v103, v122, vcc
	v_sub_f32_e32 v171, v131, v182
	v_cmp_gt_i32_e32 vcc, v206, v135
	v_add_f32_e32 v96, v96, v171
	s_and_b64 vcc, s[4:5], vcc
	v_cndmask_b32_e32 v96, v96, v122, vcc
	v_sub_f32_e32 v171, v131, v183
	v_cmp_gt_i32_e32 vcc, v207, v135
	v_add_f32_e32 v97, v97, v171
	s_and_b64 vcc, s[4:5], vcc
	v_cndmask_b32_e32 v97, v97, v122, vcc
	v_sub_f32_e32 v171, v131, v184
	v_cmp_gt_i32_e32 vcc, v168, v135
	v_max3_f32 v170, v170, v162, v163
	v_add_f32_e32 v98, v98, v171
	s_and_b64 vcc, s[4:5], vcc
	v_max3_f32 v170, v170, v100, v101
	v_cndmask_b32_e32 v98, v98, v122, vcc
	v_sub_f32_e32 v168, v131, v185
	v_cmp_gt_i32_e32 vcc, v169, v135
	v_max3_f32 v170, v170, v102, v103
	v_add_f32_e32 v99, v99, v168
	s_and_b64 vcc, s[4:5], vcc
	v_max3_f32 v170, v170, v96, v97
	v_cndmask_b32_e32 v99, v99, v122, vcc
; __device__ __forceinline__ void phase_fox_attn(const Params& p, char* smem) {
;     ...
; #pragma unroll
;       for (int qb = 0; qb < 2; ++qb) {
;         const int qpos = q0 + wave * 32 + qb * 16 + lr;
;         float mx = -INFINITY;
; #pragma unroll
;         for (int kb = 0; kb < 4; ++kb)
; #pragma unroll
;           for (int r = 0; r < 4; ++r) {
;             int kl = kb * 16 + g * 4 + r;
;             float v = s[kb][qb][r] + (ct[qb] - sCt[kl]);
;             if (diag && (kv0 + kl > qpos)) v = -INFINITY;
;             s[kb][qb][r] = v;
;             mx = fmaxf(mx, v);
;           }
;         mx = fmaxf(mx, __shfl_xor(mx, 16));
;         mx = fmaxf(mx, __shfl_xor(mx, 32));
;         mx2[qb] = mx;
;       }
;       if (__any((mx2[0] > m[0] + 8.f) || (mx2[1] > m[1] + 8.f))) {
; #pragma unroll
;         for (int qb = 0; qb < 2; ++qb) {
;           const float mnew = fmaxf(m[qb], mx2[qb]);
;           const float alpha = (mnew == -INFINITY) ? 1.f : __builtin_amdgcn_exp2f(m[qb] - mnew);
;           m[qb] = mnew;
;           l[qb] *= alpha;
; #pragma unroll
;           for (int db = 0; db < 8; ++db) { o[db][qb][0] *= alpha; o[db][qb][1] *= alpha; o[db][qb][2] *= alpha; o[db][qb][3] *= alpha; }
;         }
;       }
.Lfox_join:
	v_max3_f32 v168, v170, v98, v99
	v_add_f32_e32 v169, 0x41000000, v138
	v_cmp_gt_f32_e32 vcc, v208, v169
	v_add_f32_e32 v169, 0x41000000, v137
	v_cmp_gt_f32_e64 s[4:5], v168, v169
	s_or_b64 vcc, vcc, s[4:5]
	s_cbranch_vccz .LBB0_200
	v_mbcnt_hi_u32_b32 v171, -1, v156
	v_xor_b32_e32 v194, 16, v171
	v_lshlrev_b32_e32 v194, 2, v194
	v_xor_b32_e32 v170, 32, v171
	v_lshlrev_b32_e32 v170, 2, v170
	ds_bpermute_b32 v209, v194, v208
	ds_bpermute_b32 v169, v194, v168
	s_waitcnt lgkmcnt(0)
	v_max_f32_e32 v171, v208, v209
	v_max_f32_e32 v168, v168, v169
	ds_bpermute_b32 v172, v170, v171
	ds_bpermute_b32 v170, v170, v168
	s_waitcnt lgkmcnt(0)
	v_max_f32_e32 v169, v171, v172
	v_max_f32_e32 v168, v168, v170
	v_max_f32_e32 v169, v169, v169
	v_max_f32_e32 v170, v138, v138
	v_max_f32_e32 v170, v170, v169
	v_max_f32_e32 v168, v168, v168
	v_max_f32_e32 v169, v137, v137
	v_sub_f32_e32 v138, v138, v170
	v_max_f32_e32 v171, v169, v168
	v_exp_f32_e32 v138, v138
	v_sub_f32_e32 v137, v137, v171
	v_exp_f32_e32 v137, v137
	v_cmp_neq_f32_e32 vcc, s0, v170
	s_nop 1
	v_cndmask_b32_e32 v169, 1.0, v138, vcc
	v_cmp_neq_f32_e32 vcc, s0, v171
	v_mov_b32_e32 v138, v169
	v_pk_mul_f32 v[50:51], v[50:51], v[138:139] op_sel_hi:[1,0]
	v_cndmask_b32_e32 v168, 1.0, v137, vcc
	v_pk_mul_f32 v[48:49], v[48:49], v[138:139] op_sel_hi:[1,0]
	v_pk_mul_f32 v[54:55], v[54:55], v[138:139] op_sel_hi:[1,0]
	v_pk_mul_f32 v[52:53], v[52:53], v[138:139] op_sel_hi:[1,0]
	v_pk_mul_f32 v[58:59], v[58:59], v[138:139] op_sel_hi:[1,0]
	v_pk_mul_f32 v[56:57], v[56:57], v[138:139] op_sel_hi:[1,0]
	v_pk_mul_f32 v[62:63], v[62:63], v[138:139] op_sel_hi:[1,0]
	v_pk_mul_f32 v[60:61], v[60:61], v[138:139] op_sel_hi:[1,0]
	v_pk_mul_f32 v[46:47], v[46:47], v[138:139] op_sel_hi:[1,0]
	v_pk_mul_f32 v[44:45], v[44:45], v[138:139] op_sel_hi:[1,0]
	v_pk_mul_f32 v[42:43], v[42:43], v[138:139] op_sel_hi:[1,0]
	v_pk_mul_f32 v[40:41], v[40:41], v[138:139] op_sel_hi:[1,0]
	v_pk_mul_f32 v[38:39], v[38:39], v[138:139] op_sel_hi:[1,0]
	v_pk_mul_f32 v[36:37], v[36:37], v[138:139] op_sel_hi:[1,0]
	v_pk_mul_f32 v[34:35], v[34:35], v[138:139] op_sel_hi:[1,0]
	v_pk_mul_f32 v[32:33], v[32:33], v[138:139] op_sel_hi:[1,0]
	v_pk_mul_f32 v[108:109], v[108:109], v[168:169]
	v_pk_mul_f32 v[30:31], v[30:31], v[168:169] op_sel_hi:[1,0]
	v_pk_mul_f32 v[28:29], v[28:29], v[168:169] op_sel_hi:[1,0]
	v_pk_mul_f32 v[26:27], v[26:27], v[168:169] op_sel_hi:[1,0]
	v_pk_mul_f32 v[24:25], v[24:25], v[168:169] op_sel_hi:[1,0]
	v_pk_mul_f32 v[22:23], v[22:23], v[168:169] op_sel_hi:[1,0]
	v_pk_mul_f32 v[20:21], v[20:21], v[168:169] op_sel_hi:[1,0]
	v_pk_mul_f32 v[18:19], v[18:19], v[168:169] op_sel_hi:[1,0]
	v_pk_mul_f32 v[16:17], v[16:17], v[168:169] op_sel_hi:[1,0]
	v_pk_mul_f32 v[14:15], v[14:15], v[168:169] op_sel_hi:[1,0]
	v_pk_mul_f32 v[12:13], v[12:13], v[168:169] op_sel_hi:[1,0]
	v_pk_mul_f32 v[10:11], v[10:11], v[168:169] op_sel_hi:[1,0]
	v_pk_mul_f32 v[8:9], v[8:9], v[168:169] op_sel_hi:[1,0]
	v_pk_mul_f32 v[6:7], v[6:7], v[168:169] op_sel_hi:[1,0]
	v_pk_mul_f32 v[4:5], v[4:5], v[168:169] op_sel_hi:[1,0]
	v_pk_mul_f32 v[2:3], v[2:3], v[168:169] op_sel_hi:[1,0]
	v_pk_mul_f32 v[0:1], v[0:1], v[168:169] op_sel_hi:[1,0]
	v_mov_b32_e32 v137, v171
	v_mov_b32_e32 v138, v170
	s_branch .LBB0_200
.Lfox_fast:
	s_waitcnt lgkmcnt(0)
	v_sub_f32_e32 v139, v130, v186
	v_add_f32_e32 v139, v178, v139
	v_sub_f32_e32 v143, v130, v187
	v_add_f32_e32 v143, v179, v143
	v_sub_f32_e32 v145, v130, v188
	v_add_f32_e32 v145, v180, v145
	v_sub_f32_e32 v146, v130, v189
	v_add_f32_e32 v146, v181, v146
	v_max3_f32 v147, v139, s0, v143
	v_max3_f32 v149, v147, v145, v146
	v_sub_f32_e32 v147, v130, v190
	v_add_f32_e32 v147, v182, v147
	v_sub_f32_e32 v148, v130, v191
	v_add_f32_e32 v148, v183, v148
	ds_read_b128 v[178:181], v151 offset:128
	v_max3_f32 v152, v149, v147, v148
	v_sub_f32_e32 v149, v130, v192
	v_add_f32_e32 v149, v184, v149
	v_sub_f32_e32 v150, v130, v193
	v_add_f32_e32 v150, v185, v150
	ds_read_b128 v[182:185], v151 offset:192
	s_waitcnt lgkmcnt(0)
	v_sub_f32_e32 v151, v130, v178
	v_add_f32_e32 v151, v162, v151
	v_max3_f32 v153, v152, v149, v150
	v_sub_f32_e32 v152, v130, v179
	v_add_f32_e32 v152, v163, v152
	v_max3_f32 v155, v153, v151, v152
	v_sub_f32_e32 v153, v130, v180
	v_add_f32_e32 v153, v164, v153
	v_sub_f32_e32 v154, v130, v181
	v_add_f32_e32 v154, v165, v154
	v_max3_f32 v158, v155, v153, v154
	v_sub_f32_e32 v155, v130, v182
	v_add_f32_e32 v155, v166, v155
	v_sub_f32_e32 v157, v130, v183
	v_add_f32_e32 v157, v167, v157
	v_max3_f32 v162, v158, v155, v157
	v_sub_f32_e32 v158, v130, v184
	v_add_f32_e32 v158, v168, v158
	v_sub_f32_e32 v163, v130, v185
	v_add_f32_e32 v159, v169, v163
	v_max3_f32 v208, v162, v158, v159
	v_sub_f32_e32 v162, v131, v186
	v_add_f32_e32 v160, v170, v162
	v_sub_f32_e32 v162, v131, v187
	v_add_f32_e32 v161, v171, v162
	v_sub_f32_e32 v163, v131, v188
	v_add_f32_e32 v164, v172, v163
	v_sub_f32_e32 v163, v131, v189
	v_add_f32_e32 v165, v173, v163
	v_sub_f32_e32 v163, v131, v190
	v_add_f32_e32 v166, v174, v163
	v_sub_f32_e32 v163, v131, v191
	v_max3_f32 v162, v160, s0, v161
	v_add_f32_e32 v167, v175, v163
	v_max3_f32 v162, v162, v164, v165
	v_max3_f32 v170, v162, v166, v167
	v_sub_f32_e32 v162, v131, v192
	v_add_f32_e32 v162, v176, v162
	v_sub_f32_e32 v163, v131, v193
	v_add_f32_e32 v163, v177, v163
	v_sub_f32_e32 v171, v131, v178
	v_add_f32_e32 v100, v100, v171
	v_sub_f32_e32 v171, v131, v179
	v_add_f32_e32 v101, v101, v171
	v_sub_f32_e32 v171, v131, v180
	v_add_f32_e32 v102, v102, v171
	v_sub_f32_e32 v171, v131, v181
	v_add_f32_e32 v103, v103, v171
	v_sub_f32_e32 v171, v131, v182
	v_add_f32_e32 v96, v96, v171
	v_sub_f32_e32 v171, v131, v183
	v_add_f32_e32 v97, v97, v171
	v_sub_f32_e32 v171, v131, v184
	v_max3_f32 v170, v170, v162, v163
	v_add_f32_e32 v98, v98, v171
	v_max3_f32 v170, v170, v100, v101
	v_sub_f32_e32 v168, v131, v185
	v_max3_f32 v170, v170, v102, v103
	v_add_f32_e32 v99, v99, v168
	v_max3_f32 v170, v170, v96, v97
	s_branch .Lfox_join
